# band attention bias gather: index pre-scaled by 4 (drops 32 shift-adds per near tile) and no-clamp variant for chunk distance 0/1 (drops the 32 mins too)
# baseline (speedup 1.0000x reference)
.LBB0_454:
	s_cmp_le_i32 s23, s62
	s_cselect_b64 s[60:61], -1, 0
	s_cmp_ge_i32 s23, s63
	s_cselect_b64 s[66:67], -1, 0
	s_and_b64 s[60:61], s[60:61], s[66:67]
	s_andn2_b64 vcc, exec, s[60:61]
	s_cbranch_vccnz .LBB0_462
	ds_read_b128 v[4:7], v165
	ds_read_b128 v[8:11], v165 offset:32
	ds_read_b128 v[12:15], v165 offset:4608
	ds_read_b128 v[130:133], v165 offset:64
	ds_read_b128 v[134:137], v165 offset:4640
	ds_read_b128 v[138:141], v165 offset:4672
	s_waitcnt lgkmcnt(5)
	v_mfma_f32_32x32x16_bf16 v[50:65], v[4:7], v[82:85], 0
	ds_read_b128 v[4:7], v165 offset:96
	ds_read_b128 v[142:145], v165 offset:4704
	s_waitcnt lgkmcnt(5)
	v_mfma_f32_32x32x16_bf16 v[66:81], v[12:15], v[82:85], 0
	v_mfma_f32_32x32x16_bf16 v[50:65], v[8:11], v[86:89], v[50:65]
	s_waitcnt lgkmcnt(3)
	v_mfma_f32_32x32x16_bf16 v[66:81], v[134:137], v[86:89], v[66:81]
	v_mfma_f32_32x32x16_bf16 v[50:65], v[130:133], v[90:93], v[50:65]
	s_waitcnt lgkmcnt(2)
	v_mfma_f32_32x32x16_bf16 v[66:81], v[138:141], v[90:93], v[66:81]
	s_waitcnt lgkmcnt(1)
	v_mfma_f32_32x32x16_bf16 v[50:65], v[4:7], v[94:97], v[50:65]
	s_waitcnt lgkmcnt(0)
	v_mfma_f32_32x32x16_bf16 v[66:81], v[142:145], v[94:97], v[66:81]
	s_cmp_lt_i32 s64, 3
	s_mov_b64 s[60:61], -1
	s_cbranch_scc0 .LBB0_457
	v_lshlrev_b32_e32 v186, 2, v119
	s_cmp_lt_i32 s64, 2
	s_cbranch_scc0 .Lbg_clamp
	ds_read_b32 v4, v186 offset:21504
	ds_read_b32 v5, v186 offset:21500
	ds_read_b32 v6, v186 offset:21496
	ds_read_b32 v7, v186 offset:21492
	ds_read_b32 v8, v186 offset:21488
	ds_read_b32 v9, v186 offset:21484
	ds_read_b32 v10, v186 offset:21480
	ds_read_b32 v11, v186 offset:21476
	ds_read_b32 v12, v186 offset:21440
	ds_read_b32 v13, v186 offset:21436
	ds_read_b32 v14, v186 offset:21432
	ds_read_b32 v15, v186 offset:21428
	ds_read_b32 v130, v186 offset:21424
	ds_read_b32 v131, v186 offset:21420
	ds_read_b32 v16, v186 offset:21416
	ds_read_b32 v17, v186 offset:21412
	ds_read_b32 v136, v186 offset:21376
	ds_read_b32 v137, v186 offset:21372
	ds_read_b32 v132, v186 offset:21368
	ds_read_b32 v133, v186 offset:21364
	ds_read_b32 v174, v186 offset:21360
	ds_read_b32 v175, v186 offset:21356
	ds_read_b32 v176, v186 offset:21352
	ds_read_b32 v177, v186 offset:21348
	ds_read_b32 v178, v186 offset:21312
	ds_read_b32 v179, v186 offset:21308
	ds_read_b32 v180, v186 offset:21304
	ds_read_b32 v181, v186 offset:21300
	ds_read_b32 v182, v186 offset:21296
	ds_read_b32 v183, v186 offset:21292
	ds_read_b32 v184, v186 offset:21288
	ds_read_b32 v185, v186 offset:21284
	s_branch .Lbg_tail
.Lbg_clamp:
	v_min_i32_e32 v5, 0x404, v186
	v_min_i32_e32 v6, 0x408, v186
	v_min_i32_e32 v7, 0x40c, v186
	v_min_i32_e32 v13, 0x444, v186
	v_min_i32_e32 v8, 0x410, v186
	v_min_i32_e32 v14, 0x448, v186
	v_min_i32_e32 v9, 0x414, v186
	v_min_i32_e32 v15, 0x44c, v186
	v_min_i32_e32 v10, 0x418, v186
	v_min_i32_e32 v16, 0x450, v186
	v_min_i32_e32 v2, 0x400, v186
	v_min_i32_e32 v11, 0x41c, v186
	v_min_i32_e32 v17, 0x454, v186
	ds_read_b32 v4, v2 offset:21504
	ds_read_b32 v5, v5 offset:21500
	ds_read_b32 v6, v6 offset:21496
	ds_read_b32 v7, v7 offset:21492
	ds_read_b32 v8, v8 offset:21488
	ds_read_b32 v9, v9 offset:21484
	ds_read_b32 v10, v10 offset:21480
	ds_read_b32 v11, v11 offset:21476
	v_min_i32_e32 v129, 0x458, v186
	v_min_i32_e32 v2, 0x440, v186
	v_min_i32_e32 v132, 0x45c, v186
	ds_read_b32 v12, v2 offset:21440
	ds_read_b32 v13, v13 offset:21436
	ds_read_b32 v14, v14 offset:21432
	ds_read_b32 v15, v15 offset:21428
	ds_read_b32 v130, v16 offset:21424
	ds_read_b32 v131, v17 offset:21420
	ds_read_b32 v16, v129 offset:21416
	ds_read_b32 v17, v132 offset:21412
	v_min_i32_e32 v2, 0x480, v186
	v_min_i32_e32 v132, 0x488, v186
	v_min_i32_e32 v133, 0x48c, v186
	v_min_i32_e32 v138, 0x498, v186
	v_min_i32_e32 v129, 0x484, v186
	v_min_i32_e32 v134, 0x490, v186
	v_min_i32_e32 v135, 0x494, v186
	v_min_i32_e32 v139, 0x49c, v186
	ds_read_b32 v136, v2 offset:21376
	ds_read_b32 v137, v129 offset:21372
	ds_read_b32 v132, v132 offset:21368
	ds_read_b32 v133, v133 offset:21364
	ds_read_b32 v174, v134 offset:21360
	ds_read_b32 v175, v135 offset:21356
	ds_read_b32 v176, v138 offset:21352
	ds_read_b32 v177, v139 offset:21348
	v_min_i32_e32 v2, 0x4c0, v186
	v_min_i32_e32 v129, 0x4c4, v186
	v_min_i32_e32 v134, 0x4c8, v186
	v_min_i32_e32 v135, 0x4cc, v186
	v_min_i32_e32 v138, 0x4d0, v186
	v_min_i32_e32 v139, 0x4d4, v186
	v_min_i32_e32 v140, 0x4d8, v186
	v_min_i32_e32 v141, 0x4dc, v186
	ds_read_b32 v178, v2 offset:21312
	ds_read_b32 v179, v129 offset:21308
	ds_read_b32 v180, v134 offset:21304
	ds_read_b32 v181, v135 offset:21300
	ds_read_b32 v182, v138 offset:21296
	ds_read_b32 v183, v139 offset:21292
	ds_read_b32 v184, v140 offset:21288
	ds_read_b32 v185, v141 offset:21284
.Lbg_tail:
	s_waitcnt lgkmcnt(14)
	v_pk_add_f32 v[16:17], v[64:65], v[16:17]
	v_pk_add_f32 v[130:131], v[62:63], v[130:131]
	v_pk_add_f32 v[134:135], v[60:61], v[14:15]
	v_pk_add_f32 v[138:139], v[58:59], v[12:13]
	v_pk_add_f32 v[140:141], v[56:57], v[10:11]
	v_pk_add_f32 v[142:143], v[54:55], v[8:9]
	v_pk_add_f32 v[144:145], v[52:53], v[6:7]
	v_pk_add_f32 v[146:147], v[50:51], v[4:5]
	s_waitcnt lgkmcnt(0)
	v_pk_add_f32 v[4:5], v[80:81], v[184:185]
	v_pk_add_f32 v[6:7], v[78:79], v[182:183]
	v_pk_add_f32 v[8:9], v[76:77], v[180:181]
	v_pk_add_f32 v[10:11], v[74:75], v[178:179]
	v_pk_add_f32 v[12:13], v[72:73], v[176:177]
	v_pk_add_f32 v[14:15], v[70:71], v[174:175]
	v_pk_add_f32 v[132:133], v[68:69], v[132:133]
	v_pk_add_f32 v[136:137], v[66:67], v[136:137]
	s_mov_b64 s[60:61], 0
